# lever 1: MLA fast loop counted wait: V ds_write waits vmcnt(1) (V load only), the second K LDS-DMA piece is waited with the pre-barrier lgkmcnt wait
# baseline (speedup 1.0000x reference)
; #define AT_QK_LD0(kb_) do { if constexpr (NEGM) { const LAS unsigned char* kbp_ = Kl + (kb_) * KBUF + r32 * KROWB + hi * 16; AT_KLD2(0); __builtin_amdgcn_sched_barrier(0); } } while (0)
; template <int DQK, int DV, int RH, bool NEGM> ...
;     ...
;         for (int t = 0; t < NT; ++t) {
;             const int kb = t & 1;
;             if (t + 1 < NT) AT_GLOAD(t + 1);
;             f32x16 p[RH][2];
;             AT_QK_LD0(kb); AT_QK(kb); AT_VLOAD(vs_cur); AT_SOFTMAX(); AT_PV(vs_cur);
;             if (t + 1 < NT) AT_LSTORE(kb ^ 1, vs_next);
;             __syncthreads();
;             vs_prev = vs_cur; vs_cur = vs_next; vs_next = (vs_next == 2) ? 0 : vs_next + 1;
.Lmla_loop:
	ds_read_b128 v[48:51], v169 offset:13312
	ds_read_b128 v[52:55], v169 offset:13344
	ds_read_b128 v[116:119], v169 offset:19968
	ds_read_b128 v[120:123], v169 offset:20000
	s_mov_b32 m0, s70
	s_nop 0
	global_load_lds_dwordx4 v241, s[98:99]
	s_mov_b32 m0, s73
	global_load_dwordx4 v[112:115], v158, s[100:101]
	global_load_lds_dwordx4 v242, s[98:99]
	s_add_u32 s98, s98, 0x18000
	s_addc_u32 s99, s99, 0
	s_waitcnt lgkmcnt(3)
	v_mfma_f32_32x32x16_bf16 v[64:79], v[48:51], v[100:103], v[32:47]
	ds_read_b128 v[124:127], v169 offset:13376
	ds_read_b128 v[128:131], v169 offset:13408
	ds_read_b128 v[132:135], v169 offset:20032
	ds_read_b128 v[136:139], v169 offset:20064
	s_waitcnt lgkmcnt(4)
	v_mfma_f32_32x32x16_bf16 v[64:79], v[52:55], v[96:99], v[64:79]
	v_mfma_f32_32x32x16_bf16 v[48:63], v[116:119], v[100:103], v[32:47]
	v_mfma_f32_32x32x16_bf16 v[48:63], v[120:123], v[96:99], v[48:63]
	s_waitcnt lgkmcnt(1)
	v_mfma_f32_32x32x16_bf16 v[64:79], v[124:127], v[92:95], v[64:79]
	v_mfma_f32_32x32x16_bf16 v[48:63], v[132:135], v[92:95], v[48:63]
	v_mfma_f32_32x32x16_bf16 v[64:79], v[128:131], v[88:91], v[64:79]
	ds_read_b128 v[116:119], v169 offset:13440
	ds_read_b128 v[120:123], v169 offset:13472
	ds_read_b128 v[128:131], v169 offset:20096
	ds_read_b128 v[176:179], v169 offset:20128
	s_waitcnt lgkmcnt(3)
	v_mfma_f32_32x32x16_bf16 v[48:63], v[136:139], v[88:91], v[48:63]
	v_mfma_f32_32x32x16_bf16 v[64:79], v[116:119], v[84:87], v[64:79]
	ds_read_b128 v[136:139], v170 offset:35840
	ds_read_b128 v[124:127], v170 offset:35872
	s_waitcnt lgkmcnt(3)
	v_mfma_f32_32x32x16_bf16 v[48:63], v[128:131], v[84:87], v[48:63]
	v_mfma_f32_32x32x16_bf16 v[64:79], v[120:123], v[80:83], v[64:79]
	ds_read_b128 v[132:135], v170 offset:35904
	ds_read_b128 v[120:123], v170 offset:35936
	ds_read_b128 v[144:147], v170 offset:40448
	ds_read_b128 v[140:143], v170 offset:40480
	ds_read_b128 v[128:131], v170 offset:40512
	ds_read_b128 v[116:119], v170 offset:40544
	s_waitcnt lgkmcnt(8)
	v_mfma_f32_32x32x16_bf16 v[48:63], v[176:179], v[80:83], v[48:63]
	s_add_i32 s43, s43, 1
	s_nop 3
	v_exp_f32_e32 v160, v64
	v_exp_f32_e32 v161, v65
	v_exp_f32_e32 v64, v66
	v_exp_f32_e32 v65, v67
	v_exp_f32_e32 v68, v68
	v_exp_f32_e32 v69, v69
	v_exp_f32_e32 v66, v70
	v_exp_f32_e32 v67, v71
	v_cvt_pk_bf16_f32 v176, v160, v161
	v_cvt_pk_bf16_f32 v177, v64, v65
	v_cvt_pk_bf16_f32 v178, v68, v69
	v_cvt_pk_bf16_f32 v179, v66, v67
	v_exp_f32_e32 v70, v74
	v_exp_f32_e32 v71, v75
	s_waitcnt lgkmcnt(0)
	v_mfma_f32_32x32x16_bf16 v[16:31], v[136:139], v[176:179], v[16:31]
	v_exp_f32_e32 v136, v72
	v_exp_f32_e32 v137, v73
	v_exp_f32_e32 v74, v76
	v_exp_f32_e32 v75, v77
	v_exp_f32_e32 v72, v78
	v_exp_f32_e32 v73, v79
	v_exp_f32_e32 v76, v48
	v_mfma_f32_32x32x16_bf16 v[0:15], v[144:147], v[176:179], v[0:15]
	v_cvt_pk_bf16_f32 v144, v136, v137
	v_cvt_pk_bf16_f32 v145, v70, v71
	v_cvt_pk_bf16_f32 v146, v74, v75
	v_cvt_pk_bf16_f32 v147, v72, v73
	v_exp_f32_e32 v77, v49
	v_exp_f32_e32 v48, v50
	v_exp_f32_e32 v49, v51
	v_mfma_f32_32x32x16_bf16 v[16:31], v[124:127], v[144:147], v[16:31]
	v_exp_f32_e32 v52, v52
	v_exp_f32_e32 v53, v53
	v_exp_f32_e32 v50, v54
	v_exp_f32_e32 v51, v55
	v_cvt_pk_bf16_f32 v124, v76, v77
	v_cvt_pk_bf16_f32 v125, v48, v49
	v_cvt_pk_bf16_f32 v126, v52, v53
	v_mfma_f32_32x32x16_bf16 v[0:15], v[140:143], v[144:147], v[0:15]
	v_cvt_pk_bf16_f32 v127, v50, v51
	v_exp_f32_e32 v78, v56
	v_exp_f32_e32 v79, v57
	v_exp_f32_e32 v54, v58
	v_exp_f32_e32 v55, v59
	v_exp_f32_e32 v58, v60
	v_exp_f32_e32 v59, v61
	v_mfma_f32_32x32x16_bf16 v[16:31], v[132:135], v[124:127], v[16:31]
	v_exp_f32_e32 v56, v62
	v_exp_f32_e32 v57, v63
	v_cvt_pk_bf16_f32 v60, v78, v79
	v_cvt_pk_bf16_f32 v61, v54, v55
	v_cvt_pk_bf16_f32 v62, v58, v59
	v_cvt_pk_bf16_f32 v63, v56, v57
	v_mfma_f32_32x32x16_bf16 v[0:15], v[128:131], v[124:127], v[0:15]
	v_mfma_f32_32x32x16_bf16 v[16:31], v[120:123], v[60:63], v[16:31]
	v_mfma_f32_32x32x16_bf16 v[0:15], v[116:119], v[60:63], v[0:15]
	s_waitcnt vmcnt(1)
	ds_write2_b64 v247, v[112:113], v[114:115] offset1:2
	v_pk_add_f32 v[48:49], v[64:65], v[48:49]
	v_pk_add_f32 v[60:61], v[160:161], v[76:77]
	v_pk_add_f32 v[48:49], v[152:153], v[48:49]
	v_pk_add_f32 v[50:51], v[66:67], v[50:51]
	v_pk_add_f32 v[60:61], v[150:151], v[60:61]
	v_pk_add_f32 v[52:53], v[68:69], v[52:53]
	v_pk_add_f32 v[48:49], v[50:51], v[48:49]
	v_pk_add_f32 v[50:51], v[70:71], v[54:55]
	v_pk_add_f32 v[52:53], v[52:53], v[60:61]
	v_pk_add_f32 v[60:61], v[136:137], v[78:79]
	v_pk_add_f32 v[48:49], v[50:51], v[48:49]
	v_pk_add_f32 v[50:51], v[72:73], v[56:57]
	v_pk_add_f32 v[52:53], v[60:61], v[52:53]
	v_pk_add_f32 v[58:59], v[74:75], v[58:59]
	v_pk_add_f32 v[152:153], v[50:51], v[48:49]
	v_pk_add_f32 v[150:151], v[58:59], v[52:53]
	s_waitcnt vmcnt(0) lgkmcnt(0)
	s_barrier
; #define AT_QK_LD0(kb_) do { if constexpr (NEGM) { const LAS unsigned char* kbp_ = Kl + (kb_) * KBUF + r32 * KROWB + hi * 16; AT_KLD2(0); __builtin_amdgcn_sched_barrier(0); } } while (0)
; template <int DQK, int DV, int RH, bool NEGM> ...
;     ...
;         for (int t = 0; t < NT; ++t) {
;             const int kb = t & 1;
;             if (t + 1 < NT) AT_GLOAD(t + 1);
;             f32x16 p[RH][2];
;             AT_QK_LD0(kb); AT_QK(kb); AT_VLOAD(vs_cur); AT_SOFTMAX(); AT_PV(vs_cur);
;             if (t + 1 < NT) AT_LSTORE(kb ^ 1, vs_next);
;             __syncthreads();
;             vs_prev = vs_cur; vs_cur = vs_next; vs_next = (vs_next == 2) ? 0 : vs_next + 1;
	ds_read_b128 v[48:51], v169
	ds_read_b128 v[52:55], v169 offset:32
	ds_read_b128 v[116:119], v169 offset:6656
	ds_read_b128 v[120:123], v169 offset:6688
	s_add_i32 m0, s70, 13312
	s_nop 0
	global_load_lds_dwordx4 v241, s[98:99]
	s_add_i32 m0, s73, s74
	global_load_dwordx4 v[112:115], v158, s[100:101] offset:128
	global_load_lds_dwordx4 v242, s[98:99]
	s_add_u32 s98, s98, 0x18000
	s_addc_u32 s99, s99, 0
	s_waitcnt lgkmcnt(3)
	v_mfma_f32_32x32x16_bf16 v[64:79], v[48:51], v[100:103], v[32:47]
	ds_read_b128 v[124:127], v169 offset:64
	ds_read_b128 v[128:131], v169 offset:96
	ds_read_b128 v[132:135], v169 offset:6720
	ds_read_b128 v[136:139], v169 offset:6752
	s_waitcnt lgkmcnt(4)
	v_mfma_f32_32x32x16_bf16 v[64:79], v[52:55], v[96:99], v[64:79]
	v_mfma_f32_32x32x16_bf16 v[48:63], v[116:119], v[100:103], v[32:47]
	v_mfma_f32_32x32x16_bf16 v[48:63], v[120:123], v[96:99], v[48:63]
	s_waitcnt lgkmcnt(1)
	v_mfma_f32_32x32x16_bf16 v[64:79], v[124:127], v[92:95], v[64:79]
	v_mfma_f32_32x32x16_bf16 v[48:63], v[132:135], v[92:95], v[48:63]
	v_mfma_f32_32x32x16_bf16 v[64:79], v[128:131], v[88:91], v[64:79]
	ds_read_b128 v[116:119], v169 offset:128
	ds_read_b128 v[120:123], v169 offset:160
	ds_read_b128 v[128:131], v169 offset:6784
	ds_read_b128 v[176:179], v169 offset:6816
	s_waitcnt lgkmcnt(3)
	v_mfma_f32_32x32x16_bf16 v[48:63], v[136:139], v[88:91], v[48:63]
	v_mfma_f32_32x32x16_bf16 v[64:79], v[116:119], v[84:87], v[64:79]
	ds_read_b128 v[136:139], v170 offset:45056
	ds_read_b128 v[124:127], v170 offset:45088
	s_waitcnt lgkmcnt(3)
	v_mfma_f32_32x32x16_bf16 v[48:63], v[128:131], v[84:87], v[48:63]
	v_mfma_f32_32x32x16_bf16 v[64:79], v[120:123], v[80:83], v[64:79]
	ds_read_b128 v[132:135], v170 offset:45120
	ds_read_b128 v[120:123], v170 offset:45152
	ds_read_b128 v[144:147], v170 offset:49664
	ds_read_b128 v[140:143], v170 offset:49696
	ds_read_b128 v[128:131], v170 offset:49728
	ds_read_b128 v[116:119], v170 offset:49760
	s_waitcnt lgkmcnt(8)
	v_mfma_f32_32x32x16_bf16 v[48:63], v[176:179], v[80:83], v[48:63]
	s_add_i32 s43, s43, 1
	s_nop 3
	v_exp_f32_e32 v160, v64
	v_exp_f32_e32 v161, v65
	v_exp_f32_e32 v64, v66
	v_exp_f32_e32 v65, v67
	v_exp_f32_e32 v68, v68
	v_exp_f32_e32 v69, v69
	v_exp_f32_e32 v66, v70
	v_exp_f32_e32 v67, v71
	v_cvt_pk_bf16_f32 v176, v160, v161
	v_cvt_pk_bf16_f32 v177, v64, v65
	v_cvt_pk_bf16_f32 v178, v68, v69
	v_cvt_pk_bf16_f32 v179, v66, v67
	v_exp_f32_e32 v70, v74
	v_exp_f32_e32 v71, v75
	s_waitcnt lgkmcnt(0)
	v_mfma_f32_32x32x16_bf16 v[16:31], v[136:139], v[176:179], v[16:31]
	v_exp_f32_e32 v136, v72
	v_exp_f32_e32 v137, v73
	v_exp_f32_e32 v74, v76
	v_exp_f32_e32 v75, v77
	v_exp_f32_e32 v72, v78
	v_exp_f32_e32 v73, v79
	v_exp_f32_e32 v76, v48
	v_mfma_f32_32x32x16_bf16 v[0:15], v[144:147], v[176:179], v[0:15]
	v_cvt_pk_bf16_f32 v144, v136, v137
	v_cvt_pk_bf16_f32 v145, v70, v71
	v_cvt_pk_bf16_f32 v146, v74, v75
	v_cvt_pk_bf16_f32 v147, v72, v73
	v_exp_f32_e32 v77, v49
	v_exp_f32_e32 v48, v50
	v_exp_f32_e32 v49, v51
	v_mfma_f32_32x32x16_bf16 v[16:31], v[124:127], v[144:147], v[16:31]
	v_exp_f32_e32 v52, v52
	v_exp_f32_e32 v53, v53
	v_exp_f32_e32 v50, v54
	v_exp_f32_e32 v51, v55
	v_cvt_pk_bf16_f32 v124, v76, v77
	v_cvt_pk_bf16_f32 v125, v48, v49
	v_cvt_pk_bf16_f32 v126, v52, v53
	v_mfma_f32_32x32x16_bf16 v[0:15], v[140:143], v[144:147], v[0:15]
	v_cvt_pk_bf16_f32 v127, v50, v51
	v_exp_f32_e32 v78, v56
	v_exp_f32_e32 v79, v57
	v_exp_f32_e32 v54, v58
	v_exp_f32_e32 v55, v59
	v_exp_f32_e32 v58, v60
	v_exp_f32_e32 v59, v61
	v_mfma_f32_32x32x16_bf16 v[16:31], v[132:135], v[124:127], v[16:31]
	v_exp_f32_e32 v56, v62
	v_exp_f32_e32 v57, v63
	v_cvt_pk_bf16_f32 v60, v78, v79
	v_cvt_pk_bf16_f32 v61, v54, v55
	v_cvt_pk_bf16_f32 v62, v58, v59
	v_cvt_pk_bf16_f32 v63, v56, v57
	v_mfma_f32_32x32x16_bf16 v[0:15], v[128:131], v[124:127], v[0:15]
	v_mfma_f32_32x32x16_bf16 v[16:31], v[120:123], v[60:63], v[16:31]
	v_mfma_f32_32x32x16_bf16 v[0:15], v[116:119], v[60:63], v[0:15]
	s_waitcnt vmcnt(1)
	ds_write2_b64 v243, v[112:113], v[114:115] offset1:2
	v_pk_add_f32 v[48:49], v[64:65], v[48:49]
	v_pk_add_f32 v[60:61], v[160:161], v[76:77]
	v_pk_add_f32 v[48:49], v[152:153], v[48:49]
	v_pk_add_f32 v[50:51], v[66:67], v[50:51]
	v_pk_add_f32 v[60:61], v[150:151], v[60:61]
	v_pk_add_f32 v[52:53], v[68:69], v[52:53]
	v_pk_add_f32 v[48:49], v[50:51], v[48:49]
	v_pk_add_f32 v[50:51], v[70:71], v[54:55]
	v_pk_add_f32 v[52:53], v[52:53], v[60:61]
	v_pk_add_f32 v[60:61], v[136:137], v[78:79]
	v_pk_add_f32 v[48:49], v[50:51], v[48:49]
	v_pk_add_f32 v[50:51], v[72:73], v[56:57]
	v_pk_add_f32 v[52:53], v[60:61], v[52:53]
	v_pk_add_f32 v[58:59], v[74:75], v[58:59]
	v_pk_add_f32 v[152:153], v[50:51], v[48:49]
	v_pk_add_f32 v[150:151], v[58:59], v[52:53]
	s_cmp_lg_u32 s43, 63
	s_waitcnt vmcnt(0) lgkmcnt(0)
	s_barrier
	s_cbranch_scc0 .Lmla_exit
; #define AT_QK_LD0(kb_) do { if constexpr (NEGM) { const LAS unsigned char* kbp_ = Kl + (kb_) * KBUF + r32 * KROWB + hi * 16; AT_KLD2(0); __builtin_amdgcn_sched_barrier(0); } } while (0)
; template <int DQK, int DV, int RH, bool NEGM> ...
;     ...
;         for (int t = 0; t < NT; ++t) {
;             const int kb = t & 1;
;             if (t + 1 < NT) AT_GLOAD(t + 1);
;             f32x16 p[RH][2];
;             AT_QK_LD0(kb); AT_QK(kb); AT_VLOAD(vs_cur); AT_SOFTMAX(); AT_PV(vs_cur);
;             if (t + 1 < NT) AT_LSTORE(kb ^ 1, vs_next);
;             __syncthreads();
;             vs_prev = vs_cur; vs_cur = vs_next; vs_next = (vs_next == 2) ? 0 : vs_next + 1;
	ds_read_b128 v[48:51], v169 offset:13312
	ds_read_b128 v[52:55], v169 offset:13344
	ds_read_b128 v[116:119], v169 offset:19968
	ds_read_b128 v[120:123], v169 offset:20000
	s_mov_b32 m0, s70
	s_nop 0
	global_load_lds_dwordx4 v241, s[98:99]
	s_mov_b32 m0, s73
	global_load_dwordx4 v[112:115], v158, s[100:101] offset:256
	global_load_lds_dwordx4 v242, s[98:99]
	s_add_u32 s98, s98, 0x18000
	s_addc_u32 s99, s99, 0
	s_waitcnt lgkmcnt(3)
	v_mfma_f32_32x32x16_bf16 v[64:79], v[48:51], v[100:103], v[32:47]
	ds_read_b128 v[124:127], v169 offset:13376
	ds_read_b128 v[128:131], v169 offset:13408
	ds_read_b128 v[132:135], v169 offset:20032
	ds_read_b128 v[136:139], v169 offset:20064
	s_waitcnt lgkmcnt(4)
	v_mfma_f32_32x32x16_bf16 v[64:79], v[52:55], v[96:99], v[64:79]
	v_mfma_f32_32x32x16_bf16 v[48:63], v[116:119], v[100:103], v[32:47]
	v_mfma_f32_32x32x16_bf16 v[48:63], v[120:123], v[96:99], v[48:63]
	s_waitcnt lgkmcnt(1)
	v_mfma_f32_32x32x16_bf16 v[64:79], v[124:127], v[92:95], v[64:79]
	v_mfma_f32_32x32x16_bf16 v[48:63], v[132:135], v[92:95], v[48:63]
	v_mfma_f32_32x32x16_bf16 v[64:79], v[128:131], v[88:91], v[64:79]
	ds_read_b128 v[116:119], v169 offset:13440
	ds_read_b128 v[120:123], v169 offset:13472
	ds_read_b128 v[128:131], v169 offset:20096
	ds_read_b128 v[176:179], v169 offset:20128
	s_waitcnt lgkmcnt(3)
	v_mfma_f32_32x32x16_bf16 v[48:63], v[136:139], v[88:91], v[48:63]
	v_mfma_f32_32x32x16_bf16 v[64:79], v[116:119], v[84:87], v[64:79]
	ds_read_b128 v[136:139], v170 offset:26624
	ds_read_b128 v[124:127], v170 offset:26656
	s_waitcnt lgkmcnt(3)
	v_mfma_f32_32x32x16_bf16 v[48:63], v[128:131], v[84:87], v[48:63]
	v_mfma_f32_32x32x16_bf16 v[64:79], v[120:123], v[80:83], v[64:79]
	ds_read_b128 v[132:135], v170 offset:26688
	ds_read_b128 v[120:123], v170 offset:26720
	ds_read_b128 v[144:147], v170 offset:31232
	ds_read_b128 v[140:143], v170 offset:31264
	ds_read_b128 v[128:131], v170 offset:31296
	ds_read_b128 v[116:119], v170 offset:31328
	s_waitcnt lgkmcnt(8)
	v_mfma_f32_32x32x16_bf16 v[48:63], v[176:179], v[80:83], v[48:63]
	s_add_i32 s43, s43, 1
	s_nop 3
	v_exp_f32_e32 v160, v64
	v_exp_f32_e32 v161, v65
	v_exp_f32_e32 v64, v66
	v_exp_f32_e32 v65, v67
	v_exp_f32_e32 v68, v68
	v_exp_f32_e32 v69, v69
	v_exp_f32_e32 v66, v70
	v_exp_f32_e32 v67, v71
	v_cvt_pk_bf16_f32 v176, v160, v161
	v_cvt_pk_bf16_f32 v177, v64, v65
	v_cvt_pk_bf16_f32 v178, v68, v69
	v_cvt_pk_bf16_f32 v179, v66, v67
	v_exp_f32_e32 v70, v74
	v_exp_f32_e32 v71, v75
	s_waitcnt lgkmcnt(0)
	v_mfma_f32_32x32x16_bf16 v[16:31], v[136:139], v[176:179], v[16:31]
	v_exp_f32_e32 v136, v72
	v_exp_f32_e32 v137, v73
	v_exp_f32_e32 v74, v76
	v_exp_f32_e32 v75, v77
	v_exp_f32_e32 v72, v78
	v_exp_f32_e32 v73, v79
	v_exp_f32_e32 v76, v48
	v_mfma_f32_32x32x16_bf16 v[0:15], v[144:147], v[176:179], v[0:15]
	v_cvt_pk_bf16_f32 v144, v136, v137
	v_cvt_pk_bf16_f32 v145, v70, v71
	v_cvt_pk_bf16_f32 v146, v74, v75
	v_cvt_pk_bf16_f32 v147, v72, v73
	v_exp_f32_e32 v77, v49
	v_exp_f32_e32 v48, v50
	v_exp_f32_e32 v49, v51
	v_mfma_f32_32x32x16_bf16 v[16:31], v[124:127], v[144:147], v[16:31]
	v_exp_f32_e32 v52, v52
	v_exp_f32_e32 v53, v53
	v_exp_f32_e32 v50, v54
	v_exp_f32_e32 v51, v55
	v_cvt_pk_bf16_f32 v124, v76, v77
	v_cvt_pk_bf16_f32 v125, v48, v49
	v_cvt_pk_bf16_f32 v126, v52, v53
	v_mfma_f32_32x32x16_bf16 v[0:15], v[140:143], v[144:147], v[0:15]
	v_cvt_pk_bf16_f32 v127, v50, v51
	v_exp_f32_e32 v78, v56
	v_exp_f32_e32 v79, v57
	v_exp_f32_e32 v54, v58
	v_exp_f32_e32 v55, v59
	v_exp_f32_e32 v58, v60
	v_exp_f32_e32 v59, v61
	v_mfma_f32_32x32x16_bf16 v[16:31], v[132:135], v[124:127], v[16:31]
	v_exp_f32_e32 v56, v62
	v_exp_f32_e32 v57, v63
	v_cvt_pk_bf16_f32 v60, v78, v79
	v_cvt_pk_bf16_f32 v61, v54, v55
	v_cvt_pk_bf16_f32 v62, v58, v59
	v_cvt_pk_bf16_f32 v63, v56, v57
	v_mfma_f32_32x32x16_bf16 v[0:15], v[128:131], v[124:127], v[0:15]
	v_mfma_f32_32x32x16_bf16 v[16:31], v[120:123], v[60:63], v[16:31]
	v_mfma_f32_32x32x16_bf16 v[0:15], v[116:119], v[60:63], v[0:15]
	s_waitcnt vmcnt(1)
	ds_write2_b64 v246, v[112:113], v[114:115] offset1:2
	v_pk_add_f32 v[48:49], v[64:65], v[48:49]
	v_pk_add_f32 v[60:61], v[160:161], v[76:77]
	v_pk_add_f32 v[48:49], v[152:153], v[48:49]
	v_pk_add_f32 v[50:51], v[66:67], v[50:51]
	v_pk_add_f32 v[60:61], v[150:151], v[60:61]
	v_pk_add_f32 v[52:53], v[68:69], v[52:53]
	v_pk_add_f32 v[48:49], v[50:51], v[48:49]
	v_pk_add_f32 v[50:51], v[70:71], v[54:55]
	v_pk_add_f32 v[52:53], v[52:53], v[60:61]
	v_pk_add_f32 v[60:61], v[136:137], v[78:79]
	v_pk_add_f32 v[48:49], v[50:51], v[48:49]
	v_pk_add_f32 v[50:51], v[72:73], v[56:57]
	v_pk_add_f32 v[52:53], v[60:61], v[52:53]
	v_pk_add_f32 v[58:59], v[74:75], v[58:59]
	v_pk_add_f32 v[152:153], v[50:51], v[48:49]
	v_pk_add_f32 v[150:151], v[58:59], v[52:53]
	s_waitcnt vmcnt(0) lgkmcnt(0)
	s_barrier
; #define AT_QK_LD0(kb_) do { if constexpr (NEGM) { const LAS unsigned char* kbp_ = Kl + (kb_) * KBUF + r32 * KROWB + hi * 16; AT_KLD2(0); __builtin_amdgcn_sched_barrier(0); } } while (0)
; template <int DQK, int DV, int RH, bool NEGM> ...
;     ...
;         for (int t = 0; t < NT; ++t) {
;             const int kb = t & 1;
;             if (t + 1 < NT) AT_GLOAD(t + 1);
;             f32x16 p[RH][2];
;             AT_QK_LD0(kb); AT_QK(kb); AT_VLOAD(vs_cur); AT_SOFTMAX(); AT_PV(vs_cur);
;             if (t + 1 < NT) AT_LSTORE(kb ^ 1, vs_next);
;             __syncthreads();
;             vs_prev = vs_cur; vs_cur = vs_next; vs_next = (vs_next == 2) ? 0 : vs_next + 1;
	ds_read_b128 v[48:51], v169
	ds_read_b128 v[52:55], v169 offset:32
	ds_read_b128 v[116:119], v169 offset:6656
	ds_read_b128 v[120:123], v169 offset:6688
	s_add_i32 m0, s70, 13312
	s_nop 0
	global_load_lds_dwordx4 v241, s[98:99]
	s_add_i32 m0, s73, s74
	global_load_dwordx4 v[112:115], v158, s[100:101] offset:384
	global_load_lds_dwordx4 v242, s[98:99]
	s_add_u32 s98, s98, 0x18000
	s_addc_u32 s99, s99, 0
	s_waitcnt lgkmcnt(3)
	v_mfma_f32_32x32x16_bf16 v[64:79], v[48:51], v[100:103], v[32:47]
	ds_read_b128 v[124:127], v169 offset:64
	ds_read_b128 v[128:131], v169 offset:96
	ds_read_b128 v[132:135], v169 offset:6720
	ds_read_b128 v[136:139], v169 offset:6752
	s_waitcnt lgkmcnt(4)
	v_mfma_f32_32x32x16_bf16 v[64:79], v[52:55], v[96:99], v[64:79]
	v_mfma_f32_32x32x16_bf16 v[48:63], v[116:119], v[100:103], v[32:47]
	v_mfma_f32_32x32x16_bf16 v[48:63], v[120:123], v[96:99], v[48:63]
	s_waitcnt lgkmcnt(1)
	v_mfma_f32_32x32x16_bf16 v[64:79], v[124:127], v[92:95], v[64:79]
	v_mfma_f32_32x32x16_bf16 v[48:63], v[132:135], v[92:95], v[48:63]
	v_mfma_f32_32x32x16_bf16 v[64:79], v[128:131], v[88:91], v[64:79]
	ds_read_b128 v[116:119], v169 offset:128
	ds_read_b128 v[120:123], v169 offset:160
	ds_read_b128 v[128:131], v169 offset:6784
	ds_read_b128 v[176:179], v169 offset:6816
	s_waitcnt lgkmcnt(3)
	v_mfma_f32_32x32x16_bf16 v[48:63], v[136:139], v[88:91], v[48:63]
	v_mfma_f32_32x32x16_bf16 v[64:79], v[116:119], v[84:87], v[64:79]
	ds_read_b128 v[136:139], v170 offset:35840
	ds_read_b128 v[124:127], v170 offset:35872
	s_waitcnt lgkmcnt(3)
	v_mfma_f32_32x32x16_bf16 v[48:63], v[128:131], v[84:87], v[48:63]
	v_mfma_f32_32x32x16_bf16 v[64:79], v[120:123], v[80:83], v[64:79]
	ds_read_b128 v[132:135], v170 offset:35904
	ds_read_b128 v[120:123], v170 offset:35936
	ds_read_b128 v[144:147], v170 offset:40448
	ds_read_b128 v[140:143], v170 offset:40480
	ds_read_b128 v[128:131], v170 offset:40512
	ds_read_b128 v[116:119], v170 offset:40544
	s_waitcnt lgkmcnt(8)
	v_mfma_f32_32x32x16_bf16 v[48:63], v[176:179], v[80:83], v[48:63]
	s_add_i32 s43, s43, 1
	s_nop 3
	v_exp_f32_e32 v160, v64
	v_exp_f32_e32 v161, v65
	v_exp_f32_e32 v64, v66
	v_exp_f32_e32 v65, v67
	v_exp_f32_e32 v68, v68
	v_exp_f32_e32 v69, v69
	v_exp_f32_e32 v66, v70
	v_exp_f32_e32 v67, v71
	v_cvt_pk_bf16_f32 v176, v160, v161
	v_cvt_pk_bf16_f32 v177, v64, v65
	v_cvt_pk_bf16_f32 v178, v68, v69
	v_cvt_pk_bf16_f32 v179, v66, v67
	v_exp_f32_e32 v70, v74
	v_exp_f32_e32 v71, v75
	s_waitcnt lgkmcnt(0)
	v_mfma_f32_32x32x16_bf16 v[16:31], v[136:139], v[176:179], v[16:31]
	v_exp_f32_e32 v136, v72
	v_exp_f32_e32 v137, v73
	v_exp_f32_e32 v74, v76
	v_exp_f32_e32 v75, v77
	v_exp_f32_e32 v72, v78
	v_exp_f32_e32 v73, v79
	v_exp_f32_e32 v76, v48
	v_mfma_f32_32x32x16_bf16 v[0:15], v[144:147], v[176:179], v[0:15]
	v_cvt_pk_bf16_f32 v144, v136, v137
	v_cvt_pk_bf16_f32 v145, v70, v71
	v_cvt_pk_bf16_f32 v146, v74, v75
	v_cvt_pk_bf16_f32 v147, v72, v73
	v_exp_f32_e32 v77, v49
	v_exp_f32_e32 v48, v50
	v_exp_f32_e32 v49, v51
	v_mfma_f32_32x32x16_bf16 v[16:31], v[124:127], v[144:147], v[16:31]
	v_exp_f32_e32 v52, v52
	v_exp_f32_e32 v53, v53
	v_exp_f32_e32 v50, v54
	v_exp_f32_e32 v51, v55
	v_cvt_pk_bf16_f32 v124, v76, v77
	v_cvt_pk_bf16_f32 v125, v48, v49
	v_cvt_pk_bf16_f32 v126, v52, v53
	v_mfma_f32_32x32x16_bf16 v[0:15], v[140:143], v[144:147], v[0:15]
	v_cvt_pk_bf16_f32 v127, v50, v51
	v_exp_f32_e32 v78, v56
	v_exp_f32_e32 v79, v57
	v_exp_f32_e32 v54, v58
	v_exp_f32_e32 v55, v59
	v_exp_f32_e32 v58, v60
	v_exp_f32_e32 v59, v61
	v_mfma_f32_32x32x16_bf16 v[16:31], v[132:135], v[124:127], v[16:31]
	v_exp_f32_e32 v56, v62
	v_exp_f32_e32 v57, v63
	v_cvt_pk_bf16_f32 v60, v78, v79
	v_cvt_pk_bf16_f32 v61, v54, v55
	v_cvt_pk_bf16_f32 v62, v58, v59
	v_cvt_pk_bf16_f32 v63, v56, v57
	v_mfma_f32_32x32x16_bf16 v[0:15], v[128:131], v[124:127], v[0:15]
	v_mfma_f32_32x32x16_bf16 v[16:31], v[120:123], v[60:63], v[16:31]
	v_mfma_f32_32x32x16_bf16 v[0:15], v[116:119], v[60:63], v[0:15]
	s_waitcnt vmcnt(1)
	ds_write2_b64 v247, v[112:113], v[114:115] offset1:2
	v_pk_add_f32 v[48:49], v[64:65], v[48:49]
	v_pk_add_f32 v[60:61], v[160:161], v[76:77]
	v_pk_add_f32 v[48:49], v[152:153], v[48:49]
	v_pk_add_f32 v[50:51], v[66:67], v[50:51]
	v_pk_add_f32 v[60:61], v[150:151], v[60:61]
	v_pk_add_f32 v[52:53], v[68:69], v[52:53]
	v_pk_add_f32 v[48:49], v[50:51], v[48:49]
	v_pk_add_f32 v[50:51], v[70:71], v[54:55]
	v_pk_add_f32 v[52:53], v[52:53], v[60:61]
	v_pk_add_f32 v[60:61], v[136:137], v[78:79]
	v_pk_add_f32 v[48:49], v[50:51], v[48:49]
	v_pk_add_f32 v[50:51], v[72:73], v[56:57]
	v_pk_add_f32 v[52:53], v[60:61], v[52:53]
	v_pk_add_f32 v[58:59], v[74:75], v[58:59]
	v_pk_add_f32 v[152:153], v[50:51], v[48:49]
	v_pk_add_f32 v[150:151], v[58:59], v[52:53]
	s_waitcnt vmcnt(0) lgkmcnt(0)
	s_barrier
; #define AT_QK_LD0(kb_) do { if constexpr (NEGM) { const LAS unsigned char* kbp_ = Kl + (kb_) * KBUF + r32 * KROWB + hi * 16; AT_KLD2(0); __builtin_amdgcn_sched_barrier(0); } } while (0)
; template <int DQK, int DV, int RH, bool NEGM> ...
;     ...
;         for (int t = 0; t < NT; ++t) {
;             const int kb = t & 1;
;             if (t + 1 < NT) AT_GLOAD(t + 1);
;             f32x16 p[RH][2];
;             AT_QK_LD0(kb); AT_QK(kb); AT_VLOAD(vs_cur); AT_SOFTMAX(); AT_PV(vs_cur);
;             if (t + 1 < NT) AT_LSTORE(kb ^ 1, vs_next);
;             __syncthreads();
;             vs_prev = vs_cur; vs_cur = vs_next; vs_next = (vs_next == 2) ? 0 : vs_next + 1;
	ds_read_b128 v[48:51], v169 offset:13312
	ds_read_b128 v[52:55], v169 offset:13344
	ds_read_b128 v[116:119], v169 offset:19968
	ds_read_b128 v[120:123], v169 offset:20000
	s_mov_b32 m0, s70
	s_nop 0
	global_load_lds_dwordx4 v241, s[98:99]
	s_mov_b32 m0, s73
	global_load_dwordx4 v[112:115], v158, s[100:101] offset:512
	global_load_lds_dwordx4 v242, s[98:99]
	s_add_u32 s98, s98, 0x18000
	s_addc_u32 s99, s99, 0
	s_waitcnt lgkmcnt(3)
	v_mfma_f32_32x32x16_bf16 v[64:79], v[48:51], v[100:103], v[32:47]
	ds_read_b128 v[124:127], v169 offset:13376
	ds_read_b128 v[128:131], v169 offset:13408
	ds_read_b128 v[132:135], v169 offset:20032
	ds_read_b128 v[136:139], v169 offset:20064
	s_waitcnt lgkmcnt(4)
	v_mfma_f32_32x32x16_bf16 v[64:79], v[52:55], v[96:99], v[64:79]
	v_mfma_f32_32x32x16_bf16 v[48:63], v[116:119], v[100:103], v[32:47]
	v_mfma_f32_32x32x16_bf16 v[48:63], v[120:123], v[96:99], v[48:63]
	s_waitcnt lgkmcnt(1)
	v_mfma_f32_32x32x16_bf16 v[64:79], v[124:127], v[92:95], v[64:79]
	v_mfma_f32_32x32x16_bf16 v[48:63], v[132:135], v[92:95], v[48:63]
	v_mfma_f32_32x32x16_bf16 v[64:79], v[128:131], v[88:91], v[64:79]
	ds_read_b128 v[116:119], v169 offset:13440
	ds_read_b128 v[120:123], v169 offset:13472
	ds_read_b128 v[128:131], v169 offset:20096
	ds_read_b128 v[176:179], v169 offset:20128
	s_waitcnt lgkmcnt(3)
	v_mfma_f32_32x32x16_bf16 v[48:63], v[136:139], v[88:91], v[48:63]
	v_mfma_f32_32x32x16_bf16 v[64:79], v[116:119], v[84:87], v[64:79]
	ds_read_b128 v[136:139], v170 offset:45056
	ds_read_b128 v[124:127], v170 offset:45088
	s_waitcnt lgkmcnt(3)
	v_mfma_f32_32x32x16_bf16 v[48:63], v[128:131], v[84:87], v[48:63]
	v_mfma_f32_32x32x16_bf16 v[64:79], v[120:123], v[80:83], v[64:79]
	ds_read_b128 v[132:135], v170 offset:45120
	ds_read_b128 v[120:123], v170 offset:45152
	ds_read_b128 v[144:147], v170 offset:49664
	ds_read_b128 v[140:143], v170 offset:49696
	ds_read_b128 v[128:131], v170 offset:49728
	ds_read_b128 v[116:119], v170 offset:49760
	s_waitcnt lgkmcnt(8)
	v_mfma_f32_32x32x16_bf16 v[48:63], v[176:179], v[80:83], v[48:63]
	s_add_i32 s43, s43, 1
	s_nop 3
	v_exp_f32_e32 v160, v64
	v_exp_f32_e32 v161, v65
	v_exp_f32_e32 v64, v66
	v_exp_f32_e32 v65, v67
	v_exp_f32_e32 v68, v68
	v_exp_f32_e32 v69, v69
	v_exp_f32_e32 v66, v70
	v_exp_f32_e32 v67, v71
	v_cvt_pk_bf16_f32 v176, v160, v161
	v_cvt_pk_bf16_f32 v177, v64, v65
	v_cvt_pk_bf16_f32 v178, v68, v69
	v_cvt_pk_bf16_f32 v179, v66, v67
	v_exp_f32_e32 v70, v74
	v_exp_f32_e32 v71, v75
	s_waitcnt lgkmcnt(0)
	v_mfma_f32_32x32x16_bf16 v[16:31], v[136:139], v[176:179], v[16:31]
	v_exp_f32_e32 v136, v72
	v_exp_f32_e32 v137, v73
	v_exp_f32_e32 v74, v76
	v_exp_f32_e32 v75, v77
	v_exp_f32_e32 v72, v78
	v_exp_f32_e32 v73, v79
	v_exp_f32_e32 v76, v48
	v_mfma_f32_32x32x16_bf16 v[0:15], v[144:147], v[176:179], v[0:15]
	v_cvt_pk_bf16_f32 v144, v136, v137
	v_cvt_pk_bf16_f32 v145, v70, v71
	v_cvt_pk_bf16_f32 v146, v74, v75
	v_cvt_pk_bf16_f32 v147, v72, v73
	v_exp_f32_e32 v77, v49
	v_exp_f32_e32 v48, v50
	v_exp_f32_e32 v49, v51
	v_mfma_f32_32x32x16_bf16 v[16:31], v[124:127], v[144:147], v[16:31]
	v_exp_f32_e32 v52, v52
	v_exp_f32_e32 v53, v53
	v_exp_f32_e32 v50, v54
	v_exp_f32_e32 v51, v55
	v_cvt_pk_bf16_f32 v124, v76, v77
	v_cvt_pk_bf16_f32 v125, v48, v49
	v_cvt_pk_bf16_f32 v126, v52, v53
	v_mfma_f32_32x32x16_bf16 v[0:15], v[140:143], v[144:147], v[0:15]
	v_cvt_pk_bf16_f32 v127, v50, v51
	v_exp_f32_e32 v78, v56
	v_exp_f32_e32 v79, v57
	v_exp_f32_e32 v54, v58
	v_exp_f32_e32 v55, v59
	v_exp_f32_e32 v58, v60
	v_exp_f32_e32 v59, v61
	v_mfma_f32_32x32x16_bf16 v[16:31], v[132:135], v[124:127], v[16:31]
	v_exp_f32_e32 v56, v62
	v_exp_f32_e32 v57, v63
	v_cvt_pk_bf16_f32 v60, v78, v79
	v_cvt_pk_bf16_f32 v61, v54, v55
	v_cvt_pk_bf16_f32 v62, v58, v59
	v_cvt_pk_bf16_f32 v63, v56, v57
	v_mfma_f32_32x32x16_bf16 v[0:15], v[128:131], v[124:127], v[0:15]
	v_mfma_f32_32x32x16_bf16 v[16:31], v[120:123], v[60:63], v[16:31]
	v_mfma_f32_32x32x16_bf16 v[0:15], v[116:119], v[60:63], v[0:15]
	s_waitcnt vmcnt(1)
	ds_write2_b64 v243, v[112:113], v[114:115] offset1:2
	v_pk_add_f32 v[48:49], v[64:65], v[48:49]
	v_pk_add_f32 v[60:61], v[160:161], v[76:77]
	v_pk_add_f32 v[48:49], v[152:153], v[48:49]
	v_pk_add_f32 v[50:51], v[66:67], v[50:51]
	v_pk_add_f32 v[60:61], v[150:151], v[60:61]
	v_pk_add_f32 v[52:53], v[68:69], v[52:53]
	v_pk_add_f32 v[48:49], v[50:51], v[48:49]
	v_pk_add_f32 v[50:51], v[70:71], v[54:55]
	v_pk_add_f32 v[52:53], v[52:53], v[60:61]
	v_pk_add_f32 v[60:61], v[136:137], v[78:79]
	v_pk_add_f32 v[48:49], v[50:51], v[48:49]
	v_pk_add_f32 v[50:51], v[72:73], v[56:57]
	v_pk_add_f32 v[52:53], v[60:61], v[52:53]
	v_pk_add_f32 v[58:59], v[74:75], v[58:59]
	v_pk_add_f32 v[152:153], v[50:51], v[48:49]
	v_pk_add_f32 v[150:151], v[58:59], v[52:53]
	s_waitcnt vmcnt(0) lgkmcnt(0)
	s_barrier
; #define AT_QK_LD0(kb_) do { if constexpr (NEGM) { const LAS unsigned char* kbp_ = Kl + (kb_) * KBUF + r32 * KROWB + hi * 16; AT_KLD2(0); __builtin_amdgcn_sched_barrier(0); } } while (0)
; template <int DQK, int DV, int RH, bool NEGM> ...
;     ...
;         for (int t = 0; t < NT; ++t) {
;             const int kb = t & 1;
;             if (t + 1 < NT) AT_GLOAD(t + 1);
;             f32x16 p[RH][2];
;             AT_QK_LD0(kb); AT_QK(kb); AT_VLOAD(vs_cur); AT_SOFTMAX(); AT_PV(vs_cur);
;             if (t + 1 < NT) AT_LSTORE(kb ^ 1, vs_next);
;             __syncthreads();
;             vs_prev = vs_cur; vs_cur = vs_next; vs_next = (vs_next == 2) ? 0 : vs_next + 1;
;         }
	ds_read_b128 v[48:51], v169
	ds_read_b128 v[52:55], v169 offset:32
	ds_read_b128 v[116:119], v169 offset:6656
	ds_read_b128 v[120:123], v169 offset:6688
	s_add_i32 m0, s70, 13312
	s_nop 0
	global_load_lds_dwordx4 v241, s[98:99]
	s_add_i32 m0, s73, s74
	global_load_dwordx4 v[112:115], v158, s[100:101] offset:640
	global_load_lds_dwordx4 v242, s[98:99]
	s_add_u32 s98, s98, 0x18000
	s_addc_u32 s99, s99, 0
	s_waitcnt lgkmcnt(3)
	v_mfma_f32_32x32x16_bf16 v[64:79], v[48:51], v[100:103], v[32:47]
	ds_read_b128 v[124:127], v169 offset:64
	ds_read_b128 v[128:131], v169 offset:96
	ds_read_b128 v[132:135], v169 offset:6720
	ds_read_b128 v[136:139], v169 offset:6752
	s_waitcnt lgkmcnt(4)
	v_mfma_f32_32x32x16_bf16 v[64:79], v[52:55], v[96:99], v[64:79]
	v_mfma_f32_32x32x16_bf16 v[48:63], v[116:119], v[100:103], v[32:47]
	v_mfma_f32_32x32x16_bf16 v[48:63], v[120:123], v[96:99], v[48:63]
	s_waitcnt lgkmcnt(1)
	v_mfma_f32_32x32x16_bf16 v[64:79], v[124:127], v[92:95], v[64:79]
	v_mfma_f32_32x32x16_bf16 v[48:63], v[132:135], v[92:95], v[48:63]
	v_mfma_f32_32x32x16_bf16 v[64:79], v[128:131], v[88:91], v[64:79]
	ds_read_b128 v[116:119], v169 offset:128
	ds_read_b128 v[120:123], v169 offset:160
	ds_read_b128 v[128:131], v169 offset:6784
	ds_read_b128 v[176:179], v169 offset:6816
	s_waitcnt lgkmcnt(3)
	v_mfma_f32_32x32x16_bf16 v[48:63], v[136:139], v[88:91], v[48:63]
	v_mfma_f32_32x32x16_bf16 v[64:79], v[116:119], v[84:87], v[64:79]
	ds_read_b128 v[136:139], v170 offset:26624
	ds_read_b128 v[124:127], v170 offset:26656
	s_waitcnt lgkmcnt(3)
	v_mfma_f32_32x32x16_bf16 v[48:63], v[128:131], v[84:87], v[48:63]
	v_mfma_f32_32x32x16_bf16 v[64:79], v[120:123], v[80:83], v[64:79]
	ds_read_b128 v[132:135], v170 offset:26688
	ds_read_b128 v[120:123], v170 offset:26720
	ds_read_b128 v[144:147], v170 offset:31232
	ds_read_b128 v[140:143], v170 offset:31264
	ds_read_b128 v[128:131], v170 offset:31296
	ds_read_b128 v[116:119], v170 offset:31328
	s_waitcnt lgkmcnt(8)
	v_mfma_f32_32x32x16_bf16 v[48:63], v[176:179], v[80:83], v[48:63]
	s_add_i32 s43, s43, 1
	s_nop 3
	v_exp_f32_e32 v160, v64
	v_exp_f32_e32 v161, v65
	v_exp_f32_e32 v64, v66
	v_exp_f32_e32 v65, v67
	v_exp_f32_e32 v68, v68
	v_exp_f32_e32 v69, v69
	v_exp_f32_e32 v66, v70
	v_exp_f32_e32 v67, v71
	v_cvt_pk_bf16_f32 v176, v160, v161
	v_cvt_pk_bf16_f32 v177, v64, v65
	v_cvt_pk_bf16_f32 v178, v68, v69
	v_cvt_pk_bf16_f32 v179, v66, v67
	v_exp_f32_e32 v70, v74
	v_exp_f32_e32 v71, v75
	s_waitcnt lgkmcnt(0)
	v_mfma_f32_32x32x16_bf16 v[16:31], v[136:139], v[176:179], v[16:31]
	v_exp_f32_e32 v136, v72
	v_exp_f32_e32 v137, v73
	v_exp_f32_e32 v74, v76
	v_exp_f32_e32 v75, v77
	v_exp_f32_e32 v72, v78
	v_exp_f32_e32 v73, v79
	v_exp_f32_e32 v76, v48
	v_mfma_f32_32x32x16_bf16 v[0:15], v[144:147], v[176:179], v[0:15]
	v_cvt_pk_bf16_f32 v144, v136, v137
	v_cvt_pk_bf16_f32 v145, v70, v71
	v_cvt_pk_bf16_f32 v146, v74, v75
	v_cvt_pk_bf16_f32 v147, v72, v73
	v_exp_f32_e32 v77, v49
	v_exp_f32_e32 v48, v50
	v_exp_f32_e32 v49, v51
	v_mfma_f32_32x32x16_bf16 v[16:31], v[124:127], v[144:147], v[16:31]
	v_exp_f32_e32 v52, v52
	v_exp_f32_e32 v53, v53
	v_exp_f32_e32 v50, v54
	v_exp_f32_e32 v51, v55
	v_cvt_pk_bf16_f32 v124, v76, v77
	v_cvt_pk_bf16_f32 v125, v48, v49
	v_cvt_pk_bf16_f32 v126, v52, v53
	v_mfma_f32_32x32x16_bf16 v[0:15], v[140:143], v[144:147], v[0:15]
	v_cvt_pk_bf16_f32 v127, v50, v51
	v_exp_f32_e32 v78, v56
	v_exp_f32_e32 v79, v57
	v_exp_f32_e32 v54, v58
	v_exp_f32_e32 v55, v59
	v_exp_f32_e32 v58, v60
	v_exp_f32_e32 v59, v61
	v_mfma_f32_32x32x16_bf16 v[16:31], v[132:135], v[124:127], v[16:31]
	v_exp_f32_e32 v56, v62
	v_exp_f32_e32 v57, v63
	v_cvt_pk_bf16_f32 v60, v78, v79
	v_cvt_pk_bf16_f32 v61, v54, v55
	v_cvt_pk_bf16_f32 v62, v58, v59
	v_cvt_pk_bf16_f32 v63, v56, v57
	v_mfma_f32_32x32x16_bf16 v[0:15], v[128:131], v[124:127], v[0:15]
	v_mfma_f32_32x32x16_bf16 v[16:31], v[120:123], v[60:63], v[16:31]
	v_mfma_f32_32x32x16_bf16 v[0:15], v[116:119], v[60:63], v[0:15]
	s_waitcnt vmcnt(1)
	ds_write2_b64 v246, v[112:113], v[114:115] offset1:2
	v_pk_add_f32 v[48:49], v[64:65], v[48:49]
	v_pk_add_f32 v[60:61], v[160:161], v[76:77]
	v_pk_add_f32 v[48:49], v[152:153], v[48:49]
	v_pk_add_f32 v[50:51], v[66:67], v[50:51]
	v_pk_add_f32 v[60:61], v[150:151], v[60:61]
	v_pk_add_f32 v[52:53], v[68:69], v[52:53]
	v_pk_add_f32 v[48:49], v[50:51], v[48:49]
	v_pk_add_f32 v[50:51], v[70:71], v[54:55]
	v_pk_add_f32 v[52:53], v[52:53], v[60:61]
	v_pk_add_f32 v[60:61], v[136:137], v[78:79]
	v_pk_add_f32 v[48:49], v[50:51], v[48:49]
	v_pk_add_f32 v[50:51], v[72:73], v[56:57]
	v_pk_add_f32 v[52:53], v[60:61], v[52:53]
	v_pk_add_f32 v[58:59], v[74:75], v[58:59]
	v_pk_add_f32 v[152:153], v[50:51], v[48:49]
	v_pk_add_f32 v[150:151], v[58:59], v[52:53]
	v_max3_f32 v148, v150, v151, v152
	v_max_f32_e32 v148, v148, v153
	v_cmp_nge_f32_e32 vcc, 0x49800000, v148
	s_cbranch_vccnz .Lmla_renorm
.Lmla_renorm_back:
	s_waitcnt vmcnt(0) lgkmcnt(0)
	s_barrier
	s_add_u32 s100, s100, 0x300
	s_addc_u32 s101, s101, 0
	s_branch .Lmla_loop
